# FF2 stream-K locality: time-aligned workgroup classes (stream positions 16 apart) placed on one XCD and prompt tiles enumerated so a class works on a 3 row-panel x 4 column-tile block (A and B K-slice
# speedup vs baseline: 1.0247x; 1.0149x over previous
.LBB0_411:
	s_or_b64 exec, exec, s[0:1]
	s_cmpk_lt_i32 s2, 0x330
	s_mul_hi_i32 s0, s2, 0xa0a0a0a1
	s_cselect_b64 s[26:27], -1, 0
	s_add_i32 s0, s0, s2
	s_lshr_b32 s1, s0, 31
	s_lshr_b32 s0, s0, 9
	s_add_i32 s0, s0, s1
	s_mulk_i32 s0, 0x330
	s_sub_i32 s0, s2, s0
	s_sext_i32_i16 s1, s0
	s_bfe_u32 s1, s1, 0x3001c
	s_add_i32 s1, s0, s1
	s_sext_i32_i16 s3, s1
	s_and_b32 s1, s1, 0xfff8
	s_ashr_i32 s6, s3, 3
	s_sub_i32 s8, s0, s1
	s_sub_i32 s80, s94, 48
	s_sub_i32 s0, s2, 48
	s_cmp_gt_u32 s2, 47
	s_cselect_b32 s81, s0, 0x10000000
	s_cmpk_lt_i32 s81, 0x198
	s_cselect_b64 s[0:1], -1, 0
	v_writelane_b32 v245, s0, 3
	s_waitcnt lgkmcnt(0)
	v_mov_b32_e32 v0, 0xe0
	v_sub_co_u32_e32 v0, vcc, s2, v0
	v_writelane_b32 v245, s1, 4
	s_mul_hi_i32 s0, s81, 0xa0a0a0a1
	s_add_i32 s0, s0, s81
	s_lshr_b32 s1, s0, 31
	s_lshr_b32 s0, s0, 8
	s_add_i32 s0, s0, s1
	s_mulk_i32 s0, 0x198
	s_sub_i32 s0, s81, s0
	s_sext_i32_i16 s1, s0
	s_bfe_u32 s1, s1, 0x3001c
	s_add_i32 s1, s0, s1
	s_sext_i32_i16 s3, s1
	s_and_b32 s1, s1, 0xfff8
	s_ashr_i32 s5, s3, 3
	s_sub_i32 s7, s0, s1
	s_cmpk_lt_i32 s2, 0x110
	s_cselect_b64 s[0:1], -1, 0
	v_writelane_b32 v245, s0, 5
	s_bfe_u32 s87, s2, 0x50002
	s_lshr_b32 s3, s2, 2
	v_writelane_b32 v245, s1, 6
	s_and_b32 s0, s2, 3
	s_lshl_b32 s89, s87, 6
	s_lshl_b32 s1, s0, 2
	s_lshl_b32 s0, s0, 8
	s_cmp_lg_u32 s87, 0
	v_writelane_b32 v245, s1, 7
	s_cselect_b64 s[36:37], -1, 0
	s_cmp_eq_u32 s87, 31
	v_writelane_b32 v245, s0, 8
	s_cselect_b64 s[38:39], -1, 0
	s_lshl_b32 s0, s2, 8
	s_and_b32 s0, s0, 0x300
	s_cmp_eq_u32 s87, 0
	v_writelane_b32 v245, s0, 9
	s_cselect_b64 s[0:1], -1, 0
	v_writelane_b32 v245, s0, 10
	s_cmp_gt_u32 s87, 1
	s_movk_i32 s93, 0x67
	v_writelane_b32 v245, s1, 11
	s_cselect_b64 s[0:1], -1, 0
	v_writelane_b32 v245, s0, 12
	s_cmp_gt_u32 s87, 2
	v_mov_b32_e32 v185, 0
	v_writelane_b32 v245, s1, 13
	s_cselect_b64 s[0:1], -1, 0
	v_writelane_b32 v245, s0, 14
	s_cmp_gt_u32 s87, 3
	v_mov_b32_e32 v216, 0x358637bd
	v_writelane_b32 v245, s1, 15
	s_cselect_b64 s[0:1], -1, 0
	v_writelane_b32 v245, s0, 16
	s_cmp_gt_u32 s87, 4
	v_mov_b32_e32 v217, 0x1000
	v_writelane_b32 v245, s1, 17
	s_cselect_b64 s[0:1], -1, 0
	v_writelane_b32 v245, s0, 18
	s_cmp_gt_u32 s87, 5
	v_mov_b32_e32 v218, 0x2000
	v_writelane_b32 v245, s1, 19
	s_cselect_b64 s[0:1], -1, 0
	v_writelane_b32 v245, s0, 20
	s_cmp_gt_u32 s87, 6
	v_mov_b32_e32 v219, 0x11083000
	v_writelane_b32 v245, s1, 21
	s_cselect_b64 s[0:1], -1, 0
	v_writelane_b32 v245, s0, 22
	s_cmp_gt_u32 s87, 7
	v_mov_b32_e32 v220, 1
	v_writelane_b32 v245, s1, 23
	s_cselect_b64 s[0:1], -1, 0
	v_writelane_b32 v245, s0, 24
	s_cmp_gt_u32 s87, 8
	v_mov_b32_e32 v222, 0x3000
	v_writelane_b32 v245, s1, 25
	s_cselect_b64 s[0:1], -1, 0
	s_cmp_gt_u32 s87, 9
	s_cselect_b64 s[40:41], -1, 0
	s_cmp_gt_u32 s87, 10
	s_cselect_b64 s[42:43], -1, 0
	s_cmp_gt_u32 s87, 11
	s_cselect_b64 s[44:45], -1, 0
	s_cmp_gt_u32 s87, 12
	s_cselect_b64 s[46:47], -1, 0
	s_cmp_gt_u32 s87, 13
	v_writelane_b32 v245, s0, 26
	s_cselect_b64 s[48:49], -1, 0
	s_cmp_gt_u32 s87, 14
	v_writelane_b32 v245, s1, 27
	s_cselect_b64 s[0:1], -1, 0
	v_writelane_b32 v245, s0, 28
	s_cmp_gt_u32 s87, 15
	v_mov_b32_e32 v223, 0x2200
	v_writelane_b32 v245, s1, 29
	s_cselect_b64 s[0:1], -1, 0
	v_writelane_b32 v245, s0, 30
	s_cmp_gt_u32 s87, 16
	s_movk_i32 s90, 0x4000
	v_writelane_b32 v245, s1, 31
	s_cselect_b64 s[0:1], -1, 0
	v_writelane_b32 v245, s0, 32
	s_cmp_gt_u32 s87, 17
	s_movk_i32 s68, 0x4800
	v_writelane_b32 v245, s1, 33
	s_cselect_b64 s[0:1], -1, 0
	v_writelane_b32 v245, s0, 34
	s_cmp_gt_u32 s87, 18
	s_mov_b32 s69, 0xffff0000
	v_writelane_b32 v245, s1, 35
	s_cselect_b64 s[0:1], -1, 0
	v_writelane_b32 v245, s0, 36
	s_cmp_gt_u32 s87, 19
	s_movk_i32 s50, 0x3000
	v_writelane_b32 v245, s1, 37
	s_cselect_b64 s[0:1], -1, 0
	v_writelane_b32 v245, s0, 38
	s_cmp_gt_u32 s87, 20
	s_mov_b32 s52, 0
	v_writelane_b32 v245, s1, 39
	s_cselect_b64 s[0:1], -1, 0
	v_writelane_b32 v245, s0, 40
	s_cmp_gt_u32 s87, 21
	s_mov_b32 s97, 0
	v_writelane_b32 v245, s1, 41
	s_cselect_b64 s[0:1], -1, 0
	v_writelane_b32 v245, s0, 42
	s_cmp_gt_u32 s87, 22
	s_nop 0
	v_writelane_b32 v245, s1, 43
	s_cselect_b64 s[0:1], -1, 0
	v_writelane_b32 v245, s0, 44
	s_cmp_gt_u32 s87, 23
	s_barrier
	v_writelane_b32 v245, s1, 45
	s_cselect_b64 s[0:1], -1, 0
	v_writelane_b32 v245, s0, 46
	s_cmp_gt_u32 s87, 24
	s_nop 0
	v_writelane_b32 v245, s1, 47
	s_cselect_b64 s[0:1], -1, 0
	v_writelane_b32 v245, s0, 48
	s_cmp_gt_u32 s87, 25
	s_nop 0
	v_writelane_b32 v245, s1, 49
	s_cselect_b64 s[0:1], -1, 0
	v_writelane_b32 v245, s0, 50
	s_cmp_gt_u32 s87, 26
	s_nop 0
	v_writelane_b32 v245, s1, 51
	s_cselect_b64 s[0:1], -1, 0
	v_writelane_b32 v245, s0, 52
	s_cmp_gt_u32 s87, 27
	s_nop 0
	v_writelane_b32 v245, s1, 53
	s_cselect_b64 s[0:1], -1, 0
	v_writelane_b32 v245, s0, 54
	s_cmp_gt_u32 s87, 28
	s_nop 0
	v_writelane_b32 v245, s1, 55
	s_cselect_b64 s[0:1], -1, 0
	v_writelane_b32 v245, s0, 56
	s_cmp_gt_u32 s87, 29
	s_nop 0
	v_writelane_b32 v245, s1, 57
	s_cselect_b64 s[0:1], -1, 0
	v_writelane_b32 v245, s0, 58
	s_nop 1
	v_writelane_b32 v245, s1, 59
	v_sub_co_u32_e64 v214, s[0:1], s2, 32
	s_xor_b64 s[0:1], s[0:1], -1
	s_nop 0
	v_writelane_b32 v245, s0, 60
	s_nop 1
	v_writelane_b32 v245, s1, 61
	s_sub_i32 s0, s94, 32
	v_writelane_b32 v245, s0, 62
	s_lshl_b32 s0, s3, 6
	s_addk_i32 s0, 0x2000
	v_writelane_b32 v245, s0, 63
	s_lshl_b32 s0, s3, 3
	s_cmpk_lt_i32 s2, 0x198
	v_writelane_b32 v244, s0, 0
	s_mul_hi_i32 s0, s2, 0x78787879
	s_cselect_b64 s[10:11], -1, 0
	v_writelane_b32 v244, s10, 1
	s_lshr_b32 s1, s0, 31
	s_ashr_i32 s0, s0, 6
	v_writelane_b32 v244, s11, 2
	s_add_i32 s10, s0, s1
	s_mul_i32 s0, s10, 0x88
	s_sub_i32 s0, s2, s0
	s_bfe_u32 s1, s0, 0x3001c
	s_add_i32 s1, s0, s1
	s_and_b32 s3, s1, 0xfff8
	s_sub_i32 s9, s0, s3
	s_sext_i32_i16 s0, s1
	s_ashr_i32 s11, s10, 31
	s_ashr_i32 s14, s0, 3
	s_lshl_b64 s[0:1], s[10:11], 11
	v_writelane_b32 v244, s0, 3
	s_nop 1
	v_writelane_b32 v244, s1, 4
	s_mov_b32 s0, s10
	v_writelane_b32 v244, s0, 5
	s_nop 1
	v_writelane_b32 v244, s1, 6
	s_lshl_b64 s[0:1], s[10:11], 21
	v_writelane_b32 v244, s0, 7
	s_cmpk_lt_i32 s2, 0x88
	s_nop 0
	v_writelane_b32 v244, s1, 8
	s_cselect_b64 s[0:1], -1, 0
	v_writelane_b32 v244, s0, 9
	s_cmpk_gt_u32 s2, 0x87
	s_nop 0
	v_writelane_b32 v244, s1, 10
	s_cselect_b64 s[0:1], -1, 0
	v_writelane_b32 v244, s0, 11
	s_nop 1
	v_writelane_b32 v244, s1, 12
	s_add_i32 s0, s84, 0xfffffbc0
	v_writelane_b32 v244, s0, 13
	s_add_i32 s0, s88, 0xfffffbc0
	s_cmpk_lt_i32 s2, 0x200
	v_writelane_b32 v244, s0, 14
	s_cselect_b64 s[0:1], -1, 0
	v_writelane_b32 v244, s0, 15
	s_ashr_i32 s3, s2, 31
	s_and_b32 s12, s2, 15
	v_writelane_b32 v244, s1, 16
	s_lshr_b32 s0, s3, 23
	s_add_i32 s0, s2, s0
	s_and_b32 s0, s0, 0xfe00
	s_sub_i32 s0, s2, s0
	s_sext_i32_i16 s1, s0
	s_bfe_u32 s1, s1, 0x3001c
	s_add_i32 s1, s0, s1
	s_and_b32 s4, s1, 0xfff8
	s_sub_i32 s15, s0, s4
	s_sext_i32_i16 s0, s1
	s_ashr_i32 s16, s0, 3
	v_readfirstlane_b32 s0, v0
	s_ashr_i32 s4, s0, 4
	s_add_i32 s10, s4, 32
	s_lshl_b32 s0, s4, 5
	s_ashr_i32 s11, s10, 31
	s_lshl_b32 s13, s12, 19
	s_ashr_i32 s1, s0, 31
	s_lshl_b32 s17, s15, 6
	v_writelane_b32 v244, s13, 17
	s_lshl_b64 s[18:19], s[10:11], 19
	v_writelane_b32 v244, s18, 18
	s_cmp_gt_i32 s4, -1
	s_nop 0
	v_writelane_b32 v244, s19, 19
	s_cselect_b64 s[18:19], -1, 0
	v_writelane_b32 v244, s18, 20
	s_ashr_i32 s11, s10, 3
	s_lshl_b32 s13, s10, 8
	v_writelane_b32 v244, s19, 21
	v_writelane_b32 v244, s11, 22
	s_lshl_b32 s10, s12, 8
	v_writelane_b32 v244, s10, 23
	s_and_b32 s56, s2, 7
	s_lshr_b32 s57, s2, 3
	s_sub_i32 s57, s57, 8
	s_lshr_b32 s58, s57, 1
	s_lshl_b32 s58, s58, 4
	s_lshl_b32 s56, s56, 1
	s_add_i32 s58, s58, s56
	s_and_b32 s57, s57, 1
	s_add_i32 s58, s58, s57
	s_add_i32 s58, s58, 64
	s_sub_i32 s57, s2, 64
	s_cmpk_lt_u32 s57, 0xa0
	s_cselect_b32 s54, s58, s2
	s_mov_b32 s55, 0
	s_lshl_b32 s10, s54, 4
	s_add_i32 s11, s10, 0x1200
	s_mul_i32 s10, s54, 36
	s_add_i32 s18, s10, 0x80
	s_or_b32 s10, s13, 0x80
	v_writelane_b32 v244, s10, 24
	s_or_b32 s10, s13, 0x90
	v_writelane_b32 v244, s10, 25
	s_or_b32 s10, s13, 0xa0
	v_writelane_b32 v244, s10, 26
	v_writelane_b32 v244, s13, 27
	s_or_b32 s10, s13, 0xb0
	v_writelane_b32 v244, s10, 28
	s_add_i32 s10, s54, 1
	s_cmpk_lt_u32 s10, 0xe0
	s_cselect_b32 s12, 36, 16
	s_cmp_gt_i32 s54, 62
	s_cselect_b32 s19, s12, 38
	s_add_i32 s12, s54, 2
	s_cmpk_lt_u32 s12, 0xe0
	s_cselect_b32 s12, 36, 16
	s_cmp_gt_i32 s54, 61
	s_cselect_b32 s12, s12, 38
	s_add_i32 s20, s19, s12
	s_cmpk_gt_u32 s2, 0xdf
	s_cselect_b64 s[12:13], -1, 0
	v_writelane_b32 v244, s12, 29
	s_nop 1
	v_writelane_b32 v244, s13, 30
	s_and_b64 s[12:13], s[12:13], exec
	s_cselect_b32 s21, 16, 36
	s_cselect_b32 s22, s11, s18
	s_and_b64 s[12:13], vcc, exec
	s_cselect_b32 s11, s18, s11
	s_cmp_lt_i32 s54, 64
	s_mul_i32 s12, s54, 38
	s_cselect_b32 s13, s12, s22
	s_cselect_b32 s18, s12, s11
	s_cselect_b32 s21, 38, s21
	s_and_b32 s12, s13, 62
	s_ashr_i32 s11, s13, 6
	s_sub_i32 s12, 64, s12
	s_cmp_lt_u32 s12, s21
	v_mov_b32_e32 v0, s12
	s_cselect_b64 s[12:13], -1, 0
	v_sub_u32_e64 v0, s21, v0 clamp
	v_writelane_b32 v244, s12, 31
	s_add_i32 s11, s11, 1
	v_writelane_b32 v244, s13, 32
	s_lshr_b32 s92, s11, 2
	s_and_b32 s28, s11, 3
	s_sub_i32 s60, s11, 38
	s_mul_i32 s61, s60, 57
	s_lshr_b32 s61, s61, 9
	s_mul_i32 s62, s61, 9
	s_sub_i32 s62, s60, s62
	s_mul_i32 s62, s62, 3
	s_lshr_b32 s63, s61, 2
	s_add_i32 s62, s62, s63
	s_and_b32 s63, s61, 3
	s_cmpk_lt_u32 s11, 0x80
	s_cselect_b32 s92, s62, s92
	s_cselect_b32 s28, s63, s28
	s_sub_i32 s60, s11, 18
	s_lshr_b32 s62, s60, 2
	s_add_i32 s62, s62, 27
	s_and_b32 s63, s60, 3
	s_cmpk_lt_u32 s11, 38
	s_cselect_b32 s92, s62, s92
	s_cselect_b32 s28, s63, s28
	s_lshr_b32 s62, s11, 1
	s_mul_i32 s62, s62, 3
	s_add_i32 s62, s62, 2
	s_and_b32 s63, s11, 1
	s_add_i32 s63, s63, 2
	s_cmpk_lt_u32 s11, 18
	s_cselect_b32 s92, s62, s92
	s_cselect_b32 s28, s63, s28
	v_readfirstlane_b32 s11, v0
	s_nop 1
	v_writelane_b32 v244, s11, 33
	s_sub_i32 s11, 64, s11
	s_cmp_gt_u32 s11, s19
	s_cselect_b32 s22, 2, 1
	s_cmp_gt_u32 s11, s20
	s_cselect_b64 s[12:13], -1, 0
	s_cmp_lg_u64 s[12:13], 0
	s_addc_u32 s11, s22, 0
	v_writelane_b32 v244, s11, 34
	s_ashr_i32 s11, s10, 31
	s_lshl_b64 s[10:11], s[10:11], 17
	v_writelane_b32 v244, s10, 35
	s_lshl_b64 s[12:13], s[54:55], 17
	s_nop 0
	v_writelane_b32 v244, s11, 36
	s_sext_i32_i16 s10, s8
	s_cmp_lt_i32 s10, 0
	s_cselect_b32 s10, s93, 0x66
	s_mul_i32 s8, s10, s8
	s_add_i32 s8, s8, s6
	s_sext_i32_i16 s6, s8
	s_mulk_i32 s6, 0x2aab
	s_lshr_b32 s10, s6, 31
	s_ashr_i32 s6, s6, 21
	s_add_i32 s6, s6, s10
	s_mul_i32 s10, s6, 0xc0
	s_sext_i32_i16 s6, s6
	s_lshl_b32 s11, s6, 3
	v_writelane_b32 v244, s12, 37
	s_sub_i32 s6, 34, s11
	s_sub_i32 s10, s8, s10
	v_writelane_b32 v244, s13, 38
	s_min_u32 s12, s6, 8
	s_sext_i32_i16 s6, s7
	s_cmp_lt_i32 s6, 0
	s_cselect_b32 s6, 52, 51
	s_mul_i32 s6, s6, s7
	s_add_i32 s6, s6, s5
	s_sext_i32_i16 s5, s6
	s_mulk_i32 s5, 0x2aab
	s_lshr_b32 s7, s5, 31
	s_ashr_i32 s5, s5, 20
	s_add_i32 s5, s5, s7
	s_mul_i32 s7, s5, 0x60
	s_sext_i32_i16 s5, s5
	s_lshl_b32 s5, s5, 3
	s_sub_i32 s13, s6, s7
	s_sub_i32 s6, 34, s5
	s_min_u32 s22, s6, 8
	s_sext_i32_i16 s6, s9
	s_cmp_lt_i32 s6, 0
	s_cselect_b32 s6, 18, 17
	s_mul_i32 s6, s6, s9
	s_add_i32 s6, s6, s14
	s_sext_i32_i16 s7, s6
	s_bfe_u32 s7, s7, 0x5001a
	s_add_i32 s7, s6, s7
	s_and_b32 s8, s7, 0xffe0
	s_sub_i32 s14, s6, s8
	s_sext_i32_i16 s6, s7
	s_ashr_i32 s6, s6, 5
	s_lshl_b32 s23, s6, 3
	s_sub_i32 s6, 34, s23
	s_min_u32 s24, s6, 8
	s_sext_i32_i16 s6, s15
	s_cmp_lt_i32 s6, 0
	s_mulk_i32 s15, 0x41
	s_cselect_b32 s6, s15, s17
	s_add_i32 s6, s6, s16
	s_sext_i32_i16 s7, s6
	s_bfe_u32 s7, s7, 0x70018
	s_add_i32 s7, s6, s7
	s_and_b32 s8, s7, 0xff80
	s_sub_i32 s6, s6, s8
	s_bfe_i32 s8, s6, 0x80000
	s_bfe_u32 s8, s8, 0x3000c
	s_add_i32 s8, s6, s8
	s_and_b32 s9, s8, 0xf8
	s_sext_i32_i16 s7, s7
	s_sub_i32 s6, s6, s9
	s_and_b32 s15, s18, 62
	s_ashr_i32 s7, s7, 7
	s_bfe_i32 s8, s8, 0x80000
	s_sub_i32 s9, 64, s15
	s_lshl_b32 s7, s7, 3
	s_sext_i32_i16 s8, s8
	s_sext_i32_i8 s6, s6
	s_min_u32 s9, s9, s21
	s_add_i32 s30, s7, s6
	s_ashr_i32 s6, s8, 3
	v_writelane_b32 v244, s6, 39
	s_lshr_b32 s6, s8, 3
	s_lshr_b32 s56, s18, 6
	s_lshr_b32 s18, s56, 2
	s_and_b32 s17, s56, 3
	s_sub_i32 s60, s56, 38
	s_mul_i32 s61, s60, 57
	s_lshr_b32 s61, s61, 9
	s_mul_i32 s62, s61, 9
	s_sub_i32 s62, s60, s62
	s_mul_i32 s62, s62, 3
	s_lshr_b32 s63, s61, 2
	s_add_i32 s62, s62, s63
	s_and_b32 s63, s61, 3
	s_cmpk_lt_u32 s56, 0x80
	s_cselect_b32 s18, s62, s18
	s_cselect_b32 s17, s63, s17
	s_sub_i32 s60, s56, 18
	s_lshr_b32 s62, s60, 2
	s_add_i32 s62, s62, 27
	s_and_b32 s63, s60, 3
	s_cmpk_lt_u32 s56, 38
	s_cselect_b32 s18, s62, s18
	s_cselect_b32 s17, s63, s17
	s_lshr_b32 s62, s56, 1
	s_mul_i32 s62, s62, 3
	s_add_i32 s62, s62, 2
	s_and_b32 s63, s56, 1
	s_add_i32 s63, s63, 2
	s_cmpk_lt_u32 s56, 18
	s_cselect_b32 s18, s62, s18
	s_cselect_b32 s17, s63, s17
	s_sub_i32 s7, 64, s9
	s_cmp_gt_u32 s7, s19
	s_cselect_b32 s16, 2, 1
	s_cmp_gt_u32 s7, s20
	v_writelane_b32 v244, s9, 40
	s_cselect_b64 s[8:9], -1, 0
	s_cmp_lg_u64 s[8:9], 0
	s_addc_u32 s8, s16, 0
	s_bfe_i64 s[6:7], s[6:7], 0x100000
	s_lshl_b64 s[6:7], s[6:7], 19
	v_writelane_b32 v244, s6, 41
	s_ashr_i32 s19, s18, 31
	s_ashr_i32 s31, s30, 31
	v_writelane_b32 v244, s7, 42
	s_lshl_b32 s6, s15, 7
	v_writelane_b32 v244, s6, 43
	v_writelane_b32 v244, s17, 44
	s_lshl_b32 s6, s17, 21
	v_writelane_b32 v244, s6, 45
	s_mov_b32 s6, s18
	v_writelane_b32 v244, s6, 46
	v_cvt_f32_ubyte0_e32 v1, s12
	v_rcp_iflag_f32_e32 v2, v1
	v_writelane_b32 v244, s7, 47
	s_lshl_b64 s[6:7], s[18:19], 21
	v_writelane_b32 v244, s6, 48
	s_nop 1
	v_writelane_b32 v244, s7, 49
	s_mov_b32 s6, s30
	v_writelane_b32 v244, s6, 50
	s_nop 1
	v_writelane_b32 v244, s7, 51
	s_lshl_b64 s[6:7], s[30:31], 19
	v_writelane_b32 v244, s6, 52
	s_cmp_eq_u32 s15, 0
	s_nop 0
	v_writelane_b32 v244, s7, 53
	s_cselect_b32 s6, s8, 0
	v_writelane_b32 v244, s6, 54
	s_sext_i32_i16 s6, s10
	v_cvt_f32_i32_e32 v0, s6
	s_cselect_b32 s7, 2, 1
	s_ashr_i32 s6, s6, 30
	v_writelane_b32 v244, s7, 55
	v_mul_f32_e32 v2, v0, v2
	v_trunc_f32_e32 v2, v2
	v_fma_f32 v0, -v2, v1, v0
	s_or_b32 s8, s6, 1
	v_cmp_ge_f32_e64 s[6:7], |v0|, v1
	v_cvt_i32_f32_e32 v0, v2
	s_and_b64 s[6:7], s[6:7], exec
	s_cselect_b32 s6, s8, 0
	v_cvt_f32_ubyte0_e32 v1, s22
	v_readfirstlane_b32 s7, v0
	s_add_i32 s15, s7, s6
	s_mul_i32 s6, s15, s12
	s_sub_i32 s6, s10, s6
	s_sext_i32_i16 s6, s6
	s_add_i32 s6, s11, s6
	v_writelane_b32 v244, s6, 56
	s_sext_i32_i16 s6, s13
	v_cvt_f32_i32_e32 v0, s6
	v_rcp_iflag_f32_e32 v2, v1
	s_ashr_i32 s6, s6, 30
	s_or_b32 s8, s6, 1
	v_mul_f32_e32 v2, v0, v2
	v_trunc_f32_e32 v2, v2
	v_fma_f32 v0, -v2, v1, v0
	v_cmp_ge_f32_e64 s[6:7], |v0|, v1
	v_cvt_i32_f32_e32 v0, v2
	s_and_b64 s[6:7], s[6:7], exec
	s_cselect_b32 s6, s8, 0
	v_cvt_f32_ubyte0_e32 v1, s24
	v_readfirstlane_b32 s7, v0
	s_add_i32 s6, s7, s6
	s_mul_i32 s7, s6, s22
	s_sub_i32 s7, s13, s7
	s_sext_i32_i8 s7, s7
	s_add_i32 s10, s5, s7
	s_sext_i32_i16 s5, s14
	v_cvt_f32_i32_e32 v0, s5
	v_rcp_iflag_f32_e32 v2, v1
	s_bfe_i64 s[8:9], s[6:7], 0x80000
	s_lshl_b64 s[8:9], s[8:9], 18
	v_writelane_b32 v244, s8, 57
	s_ashr_i32 s11, s10, 31
	v_mul_f32_e32 v2, v0, v2
	v_writelane_b32 v244, s9, 58
	s_mov_b32 s8, s10
	v_writelane_b32 v244, s8, 59
	v_trunc_f32_e32 v2, v2
	v_fma_f32 v0, -v2, v1, v0
	v_writelane_b32 v244, s9, 60
	s_lshl_b64 s[8:9], s[10:11], 18
	v_writelane_b32 v244, s8, 61
	s_ashr_i32 s5, s5, 30
	s_or_b32 s5, s5, 1
	v_writelane_b32 v244, s9, 62
	v_cmp_ge_f32_e64 s[8:9], |v0|, v1
	v_cvt_i32_f32_e32 v0, v2
	s_and_b64 s[8:9], s[8:9], exec
	v_writelane_b32 v244, s26, 63
	s_sext_i32_i8 s6, s6
	s_cselect_b32 s5, s5, 0
	v_writelane_b32 v243, s27, 0
	v_writelane_b32 v243, s6, 1
	v_readfirstlane_b32 s6, v0
	s_add_i32 s6, s6, s5
	s_mul_i32 s5, s6, s24
	s_sub_i32 s5, s14, s5
	s_sext_i32_i8 s5, s5
	s_add_i32 s5, s23, s5
	s_mul_i32 s7, s95, s94
	v_writelane_b32 v243, s5, 2
	s_sext_i32_i16 s5, s15
	s_mul_i32 s95, s7, s33
	v_writelane_b32 v243, s5, 3
	s_sext_i32_i8 s5, s6
	s_bfe_i64 s[6:7], s[6:7], 0x80000
	v_writelane_b32 v243, s5, 4
	s_lshl_b64 s[6:7], s[6:7], 19
	v_writelane_b32 v243, s6, 5
	s_ashr_i32 s5, s4, 31
	s_lshl_b64 s[4:5], s[4:5], 19
	v_writelane_b32 v243, s7, 6
	v_writelane_b32 v243, s4, 7
	s_lshl_b64 s[0:1], s[0:1], 2
	s_ashr_i32 s85, s84, 31
	v_writelane_b32 v243, s5, 8
	v_writelane_b32 v243, s0, 9
	s_lshl_b32 s4, s94, 5
	v_mbcnt_lo_u32_b32 v0, -1, 0
	v_writelane_b32 v243, s1, 10
	v_writelane_b32 v243, s84, 11
	s_add_i32 s1, s84, 0xfffff800
	s_movk_i32 s0, 0x110
	v_writelane_b32 v243, s85, 12
	v_writelane_b32 v243, s1, 13
	s_lshl_b32 s1, s2, 5
	v_writelane_b32 v243, s1, 14
	s_addk_i32 s1, 0xdc00
	v_writelane_b32 v243, s1, 15
	v_writelane_b32 v243, s4, 16
	s_add_i32 s1, s4, 0xfffffc00
	v_writelane_b32 v243, s1, 17
	s_lshl_b32 s1, s94, 10
	v_writelane_b32 v243, s1, 18
	s_lshl_b32 s1, s2, 12
	v_writelane_b32 v243, s1, 19
	s_lshl_b32 s1, s94, 14
	v_writelane_b32 v243, s1, 20
	s_add_i32 s1, 0, 0x20000
	v_writelane_b32 v243, s1, 21
	s_add_i32 s1, 0, 0x20004
	v_writelane_b32 v243, s1, 22
	v_cmp_gt_i32_e64 s[0:1], s0, v214
	v_cndmask_b32_e64 v215, 0, 1, s[26:27]
	v_mbcnt_hi_u32_b32 v221, -1, v0
	v_writelane_b32 v243, s0, 23
	s_movk_i32 s33, 0x2000
	s_mov_b32 s84, s28
	v_writelane_b32 v243, s1, 24
	v_cmp_gt_u32_e64 s[0:1], 64, v195
	s_mov_b64 s[4:5], 0x80
	s_nop 0
	v_writelane_b32 v243, s0, 25
	s_nop 1
	v_writelane_b32 v243, s1, 26
	s_lshl_b64 s[0:1], s[54:55], 2
	v_writelane_b32 v243, s0, 27
	s_nop 1
	v_writelane_b32 v243, s1, 28
	v_writelane_b32 v243, s36, 29
	s_nop 1
	v_writelane_b32 v243, s37, 30
	v_writelane_b32 v243, s38, 31
	s_nop 1
	v_writelane_b32 v243, s39, 32
	v_writelane_b32 v243, s40, 33
	s_nop 1
	v_writelane_b32 v243, s41, 34
	v_writelane_b32 v243, s42, 35
	s_nop 1
	v_writelane_b32 v243, s43, 36
	v_writelane_b32 v243, s44, 37
	s_nop 1
	v_writelane_b32 v243, s45, 38
	v_writelane_b32 v243, s46, 39
	s_nop 1
	v_writelane_b32 v243, s47, 40
	v_writelane_b32 v243, s48, 41
	s_nop 1
	v_writelane_b32 v243, s49, 42
	v_writelane_b32 v243, s94, 43
	s_nop 1
	v_writelane_b32 v243, s95, 44
	v_writelane_b32 v243, s82, 45
	s_nop 1
	v_writelane_b32 v243, s83, 46
	v_writelane_b32 v243, s86, 47
	v_writelane_b32 v243, s80, 48
	v_writelane_b32 v243, s81, 49
	v_writelane_b32 v243, s87, 50
	v_writelane_b32 v243, s89, 51
	v_writelane_b32 v243, s95, 52
	s_branch .LBB0_414
